# baseline (speedup 1.0000x reference)
; #define WAIT_V(n) asm volatile("s_waitcnt vmcnt(" #n ")" ::: "memory")
; #define BAR __builtin_amdgcn_s_barrier()
; template <int N, int K, int EPI>
; __device__ __forceinline__ void gemm_phase(const bf16* __restrict__ A, const bf16* __restrict__ Bt, float* __restrict__ outf, bf16* __restrict__ outb,
;                            const float* __restrict__ ropec, const int W) {
;     ...
;   for (int vt = blockIdx.x; vt < nwg; vt += gridDim.x) {
;     int wgid = vt;
;     { int q = nwg / NXCD, r = nwg % NXCD, xcd = wgid % NXCD, off = wgid / NXCD;
;       wgid = (xcd < r ? xcd * (q + 1) : r * (q + 1) + (xcd - r) * q) + off; }
;     const int nig = WGM * nN, gid = wgid / nig, fm = gid * WGM, gsz = min(nM - fm, WGM);
;     const int pm = fm + ((wgid % nig) % gsz), pn = (wgid % nig) / gsz, brow = pm * BM, bcol = pn * BM;
;     f32x4 acc[2][2][4][2] = {};
;     bf16x8 At[4][2], B0[2][2], B1[2][2];
;     STAGE(SB(0, 0), Bt, bcol, 0); STAGE(SA(0, 0), A, brow, 0);
;     STAGE(SB(0, 1), Bt, bcol + HALF, 0); STAGE(SA(0, 1), A, brow + HALF, 0);
;     if (wr == 1) BAR;
;     WAIT_V(4); BAR;
;     STAGE(SB(1, 0), Bt, bcol, 1); STAGE(SA(1, 0), A, brow, 1); STAGE(SB(1, 1), Bt, bcol + HALF, 1);
;     WAIT_V(6); BAR;
.LBB0_50:
	s_ashr_i32 s4, s61, 31
	s_lshr_b32 s4, s4, 29
	s_add_i32 s4, s61, s4
	s_ashr_i32 s5, s4, 3
	s_and_b32 s4, s4, -8
	s_sub_i32 s4, s61, s4
	s_cmp_lt_i32 s4, 0
	s_movk_i32 s66, 0xc1
	s_cselect_b32 s66, s66, 0xc0
	s_mul_i32 s4, s66, s4
	s_add_i32 s4, s4, s5
	s_mul_hi_i32 s5, s4, 0x2aaaaaab
	s_lshr_b32 s66, s5, 31
	s_ashr_i32 s5, s5, 4
	s_add_i32 s5, s5, s66
	s_lshl_b32 s89, s5, 3
	s_mulk_i32 s5, 0x60
	s_sub_i32 s88, s4, s5
	s_bfe_i32 s4, s88, 0x80000
	s_bfe_u32 s4, s4, 0x3000c
	s_add_i32 s4, s88, s4
	s_bfe_i32 s5, s4, 0x80000
	s_sext_i32_i16 s5, s5
	s_and_b32 s4, s4, 0xf8
	s_lshr_b32 s90, s5, 3
	s_sub_i32 s4, s88, s4
	s_sext_i32_i8 s4, s4
	s_lshl_b32 s78, s90, 8
	s_add_i32 s89, s89, s4
	s_ashr_i32 s79, s78, 31
	s_lshl_b32 s80, s89, 8
	s_lshl_b64 s[4:5], s[78:79], 11
	s_add_u32 s4, s52, s4
	s_addc_u32 s5, s53, s5
	v_readfirstlane_b32 s66, v148
	s_ashr_i32 s81, s80, 31
	v_lshl_add_u64 v[0:1], s[4:5], 0, v[142:143]
	s_mov_b32 m0, s66
	v_readfirstlane_b32 s66, v149
	s_lshl_b64 s[84:85], s[80:81], 11
	global_load_lds_dwordx4 v[0:1], off
	s_mov_b32 m0, s66
	s_add_u32 s66, s56, s84
	v_lshl_add_u64 v[2:3], v[0:1], 0, s[6:7]
	s_addc_u32 s67, s57, s85
	global_load_lds_dwordx4 v[2:3], off
	v_lshl_add_u64 v[2:3], s[66:67], 0, v[142:143]
	v_readfirstlane_b32 s66, v150
	s_mov_b32 m0, s66
	v_readfirstlane_b32 s66, v151
	global_load_lds_dwordx4 v[2:3], off
	s_mov_b32 m0, s66
	s_or_b32 s66, s78, 0x80
	s_ashr_i32 s67, s66, 31
	s_lshl_b64 s[66:67], s[66:67], 11
	s_add_u32 s66, s52, s66
	v_lshl_add_u64 v[4:5], v[2:3], 0, s[6:7]
	s_addc_u32 s67, s53, s67
	global_load_lds_dwordx4 v[4:5], off
	v_lshl_add_u64 v[4:5], s[66:67], 0, v[142:143]
	v_readfirstlane_b32 s66, v152
	s_mov_b32 m0, s66
	v_readfirstlane_b32 s66, v153
	global_load_lds_dwordx4 v[4:5], off
	s_mov_b32 m0, s66
	s_or_b32 s66, s80, 0x80
	s_ashr_i32 s67, s66, 31
	s_lshl_b64 s[66:67], s[66:67], 11
	s_add_u32 s66, s56, s66
	s_addc_u32 s67, s57, s67
	v_lshl_add_u64 v[6:7], v[4:5], 0, s[6:7]
	v_lshl_add_u64 v[128:129], s[66:67], 0, v[142:143]
	v_readfirstlane_b32 s66, v154
	global_load_lds_dwordx4 v[6:7], off
	s_mov_b32 m0, s66
	v_readfirstlane_b32 s66, v155
	global_load_lds_dwordx4 v[128:129], off
	v_lshl_add_u64 v[6:7], v[128:129], 0, s[6:7]
	s_mov_b32 m0, s66
	s_and_b64 vcc, exec, s[0:1]
	global_load_lds_dwordx4 v[6:7], off
	v_readfirstlane_b32 s66, v168
	v_lshl_add_u64 v[6:7], v[0:1], 0, s[10:11]
	s_mov_b32 m0, s66
	v_readfirstlane_b32 s66, v169
	global_load_lds_dwordx4 v[6:7], off
	v_lshl_add_u64 v[0:1], v[0:1], 0, s[12:13]
	s_mov_b32 m0, s66
	v_readfirstlane_b32 s66, v156
	global_load_lds_dwordx4 v[0:1], off
	v_lshl_add_u64 v[0:1], v[2:3], 0, s[10:11]
	s_mov_b32 m0, s66
	v_readfirstlane_b32 s66, v157
	global_load_lds_dwordx4 v[0:1], off
	v_lshl_add_u64 v[0:1], v[2:3], 0, s[12:13]
	s_mov_b32 m0, s66
	v_readfirstlane_b32 s66, v170
	global_load_lds_dwordx4 v[0:1], off
	v_lshl_add_u64 v[0:1], v[4:5], 0, s[10:11]
	s_mov_b32 m0, s66
	v_readfirstlane_b32 s66, v171
	global_load_lds_dwordx4 v[0:1], off
	v_lshl_add_u64 v[0:1], v[4:5], 0, s[12:13]
	s_mov_b32 m0, s66
	s_add_u32 s84, s52, s84
	global_load_lds_dwordx4 v[0:1], off
	s_cbranch_vccnz .LBB0_52
	s_barrier
.LBB0_52:
	s_waitcnt vmcnt(10)
	s_barrier
	s_waitcnt vmcnt(6)
	v_mov_b32_e32 v0, 0
	s_addc_u32 s85, s53, s85
	s_mov_b32 s81, -2
	v_mov_b32_e32 v1, v0
	v_mov_b32_e32 v2, v0
	v_mov_b32_e32 v3, v0
	v_mov_b32_e32 v4, v0
	v_mov_b32_e32 v5, v0
	v_mov_b32_e32 v6, v0
	v_mov_b32_e32 v7, v0
	v_mov_b32_e32 v8, v0
	v_mov_b32_e32 v9, v0
	v_mov_b32_e32 v10, v0
	v_mov_b32_e32 v11, v0
	v_mov_b32_e32 v12, v0
	v_mov_b32_e32 v13, v0
	v_mov_b32_e32 v14, v0
	v_mov_b32_e32 v15, v0
	v_mov_b32_e32 v16, v0
	v_mov_b32_e32 v17, v0
	v_mov_b32_e32 v18, v0
	v_mov_b32_e32 v19, v0
	v_mov_b32_e32 v20, v0
	v_mov_b32_e32 v21, v0
	v_mov_b32_e32 v22, v0
	v_mov_b32_e32 v23, v0
	v_mov_b32_e32 v24, v0
	v_mov_b32_e32 v25, v0
	v_mov_b32_e32 v26, v0
	v_mov_b32_e32 v27, v0
	v_mov_b32_e32 v28, v0
	v_mov_b32_e32 v29, v0
	v_mov_b32_e32 v30, v0
	v_mov_b32_e32 v31, v0
	v_mov_b32_e32 v32, v0
	v_mov_b32_e32 v33, v0
	v_mov_b32_e32 v34, v0
	v_mov_b32_e32 v35, v0
	v_mov_b32_e32 v36, v0
	v_mov_b32_e32 v37, v0
	v_mov_b32_e32 v38, v0
	v_mov_b32_e32 v39, v0
	v_mov_b32_e32 v40, v0
	v_mov_b32_e32 v41, v0
	v_mov_b32_e32 v42, v0
	v_mov_b32_e32 v43, v0
	v_mov_b32_e32 v44, v0
	v_mov_b32_e32 v45, v0
	v_mov_b32_e32 v46, v0
	v_mov_b32_e32 v47, v0
	v_mov_b32_e32 v48, v0
	v_mov_b32_e32 v49, v0
	v_mov_b32_e32 v50, v0
	v_mov_b32_e32 v51, v0
	v_mov_b32_e32 v52, v0
	v_mov_b32_e32 v53, v0
	v_mov_b32_e32 v54, v0
	v_mov_b32_e32 v55, v0
	v_mov_b32_e32 v56, v0
	v_mov_b32_e32 v57, v0
	v_mov_b32_e32 v58, v0
	v_mov_b32_e32 v59, v0
	v_mov_b32_e32 v60, v0
	v_mov_b32_e32 v61, v0
	v_mov_b32_e32 v62, v0
	v_mov_b32_e32 v63, v0
	v_mov_b32_e32 v64, v0
	v_mov_b32_e32 v65, v0
	v_mov_b32_e32 v66, v0
	v_mov_b32_e32 v67, v0
	v_mov_b32_e32 v68, v0
	v_mov_b32_e32 v69, v0
	v_mov_b32_e32 v70, v0
	v_mov_b32_e32 v71, v0
	v_mov_b32_e32 v72, v0
	v_mov_b32_e32 v73, v0
	v_mov_b32_e32 v74, v0
	v_mov_b32_e32 v75, v0
	v_mov_b32_e32 v76, v0
	v_mov_b32_e32 v77, v0
	v_mov_b32_e32 v78, v0
	v_mov_b32_e32 v79, v0
	v_mov_b32_e32 v80, v0
	v_mov_b32_e32 v81, v0
	v_mov_b32_e32 v82, v0
	v_mov_b32_e32 v83, v0
	v_mov_b32_e32 v84, v0
	v_mov_b32_e32 v85, v0
	v_mov_b32_e32 v86, v0
	v_mov_b32_e32 v87, v0
	v_mov_b32_e32 v88, v0
	v_mov_b32_e32 v89, v0
	v_mov_b32_e32 v90, v0
	v_mov_b32_e32 v91, v0
	v_mov_b32_e32 v92, v0
	v_mov_b32_e32 v93, v0
	v_mov_b32_e32 v94, v0
	v_mov_b32_e32 v95, v0
	v_mov_b32_e32 v96, v0
	v_mov_b32_e32 v97, v0
	v_mov_b32_e32 v98, v0
	v_mov_b32_e32 v99, v0
	v_mov_b32_e32 v100, v0
	v_mov_b32_e32 v101, v0
	v_mov_b32_e32 v102, v0
	v_mov_b32_e32 v103, v0
	v_mov_b32_e32 v104, v0
	v_mov_b32_e32 v105, v0
	v_mov_b32_e32 v106, v0
	v_mov_b32_e32 v107, v0
	v_mov_b32_e32 v108, v0
	v_mov_b32_e32 v109, v0
	v_mov_b32_e32 v110, v0
	v_mov_b32_e32 v111, v0
	v_mov_b32_e32 v112, v0
	v_mov_b32_e32 v113, v0
	v_mov_b32_e32 v114, v0
	v_mov_b32_e32 v115, v0
	v_mov_b32_e32 v116, v0
	v_mov_b32_e32 v117, v0
	v_mov_b32_e32 v118, v0
	v_mov_b32_e32 v119, v0
	v_mov_b32_e32 v120, v0
	v_mov_b32_e32 v121, v0
	v_mov_b32_e32 v122, v0
	v_mov_b32_e32 v123, v0
	v_mov_b32_e32 v124, v0
	v_mov_b32_e32 v125, v0
	v_mov_b32_e32 v126, v0
	v_mov_b32_e32 v127, v0
	s_barrier

; #define WAIT_V(n) asm volatile("s_waitcnt vmcnt(" #n ")" ::: "memory")
; #define BAR __builtin_amdgcn_s_barrier()
; template <int N, int K, int EPI>
; __device__ __forceinline__ void gemm_phase(const bf16* __restrict__ A, const bf16* __restrict__ Bt, float* __restrict__ outf, bf16* __restrict__ outb,
;                            const float* __restrict__ ropec, const int W) {
;     ...
;   for (int vt = blockIdx.x; vt < nwg; vt += gridDim.x) {
;     int wgid = vt;
;     { int q = nwg / NXCD, r = nwg % NXCD, xcd = wgid % NXCD, off = wgid / NXCD;
;       wgid = (xcd < r ? xcd * (q + 1) : r * (q + 1) + (xcd - r) * q) + off; }
;     const int nig = WGM * nN, gid = wgid / nig, fm = gid * WGM, gsz = min(nM - fm, WGM);
;     const int pm = fm + ((wgid % nig) % gsz), pn = (wgid % nig) / gsz, brow = pm * BM, bcol = pn * BM;
;     f32x4 acc[2][2][4][2] = {};
;     bf16x8 At[4][2], B0[2][2], B1[2][2];
;     STAGE(SB(0, 0), Bt, bcol, 0); STAGE(SA(0, 0), A, brow, 0);
;     STAGE(SB(0, 1), Bt, bcol + HALF, 0); STAGE(SA(0, 1), A, brow + HALF, 0);
;     if (wr == 1) BAR;
;     WAIT_V(4); BAR;
;     STAGE(SB(1, 0), Bt, bcol, 1); STAGE(SA(1, 0), A, brow, 1); STAGE(SB(1, 1), Bt, bcol + HALF, 1);
;     WAIT_V(6); BAR;
.LBB0_156:
	s_ashr_i32 s6, s80, 3
	s_add_i32 s6, s84, s6
	s_ashr_i32 s7, s6, 31
	s_lshr_b32 s7, s7, 27
	s_add_i32 s7, s6, s7
	s_and_b32 s80, s7, 0xffe0
	s_sub_i32 s6, s6, s80
	s_bfe_i32 s80, s6, 0x80000
	s_bfe_u32 s80, s80, 0x3000c
	s_add_i32 s80, s6, s80
	s_bfe_i32 s81, s80, 0x80000
	s_and_b32 s80, s80, 0xf8
	s_sub_i32 s6, s6, s80
	s_sext_i32_i8 s6, s6
	s_lshl_b32 s7, s7, 6
	s_sext_i32_i16 s81, s81
	s_and_b32 s7, s7, 0xfffff800
	s_lshl_b32 s6, s6, 8
	s_add_i32 s6, s6, s7
	s_lshl_b32 s7, s81, 5
	s_and_b32 s90, s7, 0xffffff00
	s_ashr_i32 s91, s90, 31
	s_lshl_b64 s[84:85], s[90:91], 11
	s_add_u32 s80, s78, s84
	s_addc_u32 s81, s79, s85
	v_readfirstlane_b32 s7, v134
	v_lshl_add_u64 v[0:1], s[80:81], 0, v[128:129]
	s_mov_b32 m0, s7
	v_readfirstlane_b32 s7, v135
	global_load_lds_dwordx4 v[0:1], off
	s_mov_b32 m0, s7
	s_ashr_i32 s7, s6, 31
	s_lshl_b64 s[94:95], s[6:7], 11
	s_add_u32 s80, s56, s94
	v_lshl_add_u64 v[2:3], v[0:1], 0, s[8:9]
	s_addc_u32 s81, s57, s95
	global_load_lds_dwordx4 v[2:3], off
	v_lshl_add_u64 v[2:3], s[80:81], 0, v[128:129]
	v_readfirstlane_b32 s80, v136
	s_mov_b32 m0, s80
	v_readfirstlane_b32 s80, v137
	global_load_lds_dwordx4 v[2:3], off
	s_mov_b32 m0, s80
	s_or_b32 s80, s90, 0x80
	s_ashr_i32 s81, s80, 31
	s_lshl_b64 s[80:81], s[80:81], 11
	s_add_u32 s80, s78, s80
	v_lshl_add_u64 v[4:5], v[2:3], 0, s[8:9]
	s_addc_u32 s81, s79, s81
	global_load_lds_dwordx4 v[4:5], off
	v_lshl_add_u64 v[4:5], s[80:81], 0, v[128:129]
	v_readfirstlane_b32 s80, v138
	s_mov_b32 m0, s80
	v_readfirstlane_b32 s80, v139
	global_load_lds_dwordx4 v[4:5], off
	s_mov_b32 m0, s80
	s_or_b32 s80, s6, 0x80
	s_ashr_i32 s81, s80, 31
	s_lshl_b64 s[80:81], s[80:81], 11
	s_add_u32 s80, s56, s80
	s_addc_u32 s81, s57, s81
	v_lshl_add_u64 v[6:7], v[4:5], 0, s[8:9]
	v_lshl_add_u64 v[132:133], s[80:81], 0, v[128:129]
	v_readfirstlane_b32 s80, v140
	global_load_lds_dwordx4 v[6:7], off
	s_mov_b32 m0, s80
	v_readfirstlane_b32 s80, v141
	global_load_lds_dwordx4 v[132:133], off
	v_lshl_add_u64 v[6:7], v[132:133], 0, s[8:9]
	s_mov_b32 m0, s80
	s_and_b64 vcc, exec, s[0:1]
	global_load_lds_dwordx4 v[6:7], off
	s_lshl_b64 s[80:81], s[6:7], 10
	v_readfirstlane_b32 s6, v154
	v_lshl_add_u64 v[6:7], v[0:1], 0, s[86:87]
	s_mov_b32 m0, s6
	v_readfirstlane_b32 s6, v155
	global_load_lds_dwordx4 v[6:7], off
	v_lshl_add_u64 v[0:1], v[0:1], 0, s[88:89]
	s_mov_b32 m0, s6
	v_readfirstlane_b32 s6, v142
	global_load_lds_dwordx4 v[0:1], off
	v_lshl_add_u64 v[0:1], v[2:3], 0, s[86:87]
	s_mov_b32 m0, s6
	v_readfirstlane_b32 s6, v143
	global_load_lds_dwordx4 v[0:1], off
	v_lshl_add_u64 v[0:1], v[2:3], 0, s[88:89]
	s_mov_b32 m0, s6
	v_readfirstlane_b32 s6, v156
	global_load_lds_dwordx4 v[0:1], off
	v_lshl_add_u64 v[0:1], v[4:5], 0, s[86:87]
	s_mov_b32 m0, s6
	v_readfirstlane_b32 s6, v157
	global_load_lds_dwordx4 v[0:1], off
	v_lshl_add_u64 v[0:1], v[4:5], 0, s[88:89]
	s_mov_b32 m0, s6
	s_add_u32 s92, s52, s84
	global_load_lds_dwordx4 v[0:1], off
	s_cbranch_vccnz .LBB0_158
	s_barrier
.LBB0_158:
	s_waitcnt vmcnt(10)
	s_barrier
	s_waitcnt vmcnt(6)
	s_addc_u32 s93, s53, s85
	s_add_u32 s94, s52, s94
	v_mov_b32_e32 v0, 0
	s_addc_u32 s95, s53, s95
	s_mov_b32 s6, -2
	v_mov_b32_e32 v1, v0
	v_mov_b32_e32 v2, v0
	v_mov_b32_e32 v3, v0
	v_mov_b32_e32 v4, v0
	v_mov_b32_e32 v5, v0
	v_mov_b32_e32 v6, v0
	v_mov_b32_e32 v7, v0
	v_mov_b32_e32 v8, v0
	v_mov_b32_e32 v9, v0
	v_mov_b32_e32 v10, v0
	v_mov_b32_e32 v11, v0
	v_mov_b32_e32 v12, v0
	v_mov_b32_e32 v13, v0
	v_mov_b32_e32 v14, v0
	v_mov_b32_e32 v15, v0
	v_mov_b32_e32 v16, v0
	v_mov_b32_e32 v17, v0
	v_mov_b32_e32 v18, v0
	v_mov_b32_e32 v19, v0
	v_mov_b32_e32 v20, v0
	v_mov_b32_e32 v21, v0
	v_mov_b32_e32 v22, v0
	v_mov_b32_e32 v23, v0
	v_mov_b32_e32 v24, v0
	v_mov_b32_e32 v25, v0
	v_mov_b32_e32 v26, v0
	v_mov_b32_e32 v27, v0
	v_mov_b32_e32 v28, v0
	v_mov_b32_e32 v29, v0
	v_mov_b32_e32 v30, v0
	v_mov_b32_e32 v31, v0
	v_mov_b32_e32 v32, v0
	v_mov_b32_e32 v33, v0
	v_mov_b32_e32 v34, v0
	v_mov_b32_e32 v35, v0
	v_mov_b32_e32 v36, v0
	v_mov_b32_e32 v37, v0
	v_mov_b32_e32 v38, v0
	v_mov_b32_e32 v39, v0
	v_mov_b32_e32 v40, v0
	v_mov_b32_e32 v41, v0
	v_mov_b32_e32 v42, v0
	v_mov_b32_e32 v43, v0
	v_mov_b32_e32 v44, v0
	v_mov_b32_e32 v45, v0
	v_mov_b32_e32 v46, v0
	v_mov_b32_e32 v47, v0
	v_mov_b32_e32 v48, v0
	v_mov_b32_e32 v49, v0
	v_mov_b32_e32 v50, v0
	v_mov_b32_e32 v51, v0
	v_mov_b32_e32 v52, v0
	v_mov_b32_e32 v53, v0
	v_mov_b32_e32 v54, v0
	v_mov_b32_e32 v55, v0
	v_mov_b32_e32 v56, v0
	v_mov_b32_e32 v57, v0
	v_mov_b32_e32 v58, v0
	v_mov_b32_e32 v59, v0
	v_mov_b32_e32 v60, v0
	v_mov_b32_e32 v61, v0
	v_mov_b32_e32 v62, v0
	v_mov_b32_e32 v63, v0
	v_mov_b32_e32 v64, v0
	v_mov_b32_e32 v65, v0
	v_mov_b32_e32 v66, v0
	v_mov_b32_e32 v67, v0
	v_mov_b32_e32 v68, v0
	v_mov_b32_e32 v69, v0
	v_mov_b32_e32 v70, v0
	v_mov_b32_e32 v71, v0
	v_mov_b32_e32 v72, v0
	v_mov_b32_e32 v73, v0
	v_mov_b32_e32 v74, v0
	v_mov_b32_e32 v75, v0
	v_mov_b32_e32 v76, v0
	v_mov_b32_e32 v77, v0
	v_mov_b32_e32 v78, v0
	v_mov_b32_e32 v79, v0
	v_mov_b32_e32 v80, v0
	v_mov_b32_e32 v81, v0
	v_mov_b32_e32 v82, v0
	v_mov_b32_e32 v83, v0
	v_mov_b32_e32 v84, v0
	v_mov_b32_e32 v85, v0
	v_mov_b32_e32 v86, v0
	v_mov_b32_e32 v87, v0
	v_mov_b32_e32 v88, v0
	v_mov_b32_e32 v89, v0
	v_mov_b32_e32 v90, v0
	v_mov_b32_e32 v91, v0
	v_mov_b32_e32 v92, v0
	v_mov_b32_e32 v93, v0
	v_mov_b32_e32 v94, v0
	v_mov_b32_e32 v95, v0
	v_mov_b32_e32 v96, v0
	v_mov_b32_e32 v97, v0
	v_mov_b32_e32 v98, v0
	v_mov_b32_e32 v99, v0
	v_mov_b32_e32 v100, v0
	v_mov_b32_e32 v101, v0
	v_mov_b32_e32 v102, v0
	v_mov_b32_e32 v103, v0
	v_mov_b32_e32 v104, v0
	v_mov_b32_e32 v105, v0
	v_mov_b32_e32 v106, v0
	v_mov_b32_e32 v107, v0
	v_mov_b32_e32 v108, v0
	v_mov_b32_e32 v109, v0
	v_mov_b32_e32 v110, v0
	v_mov_b32_e32 v111, v0
	v_mov_b32_e32 v112, v0
	v_mov_b32_e32 v113, v0
	v_mov_b32_e32 v114, v0
	v_mov_b32_e32 v115, v0
	v_mov_b32_e32 v116, v0
	v_mov_b32_e32 v117, v0
	v_mov_b32_e32 v118, v0
	v_mov_b32_e32 v119, v0
	v_mov_b32_e32 v120, v0
	v_mov_b32_e32 v121, v0
	v_mov_b32_e32 v122, v0
	v_mov_b32_e32 v123, v0
	v_mov_b32_e32 v124, v0
	v_mov_b32_e32 v125, v0
	v_mov_b32_e32 v126, v0
	v_mov_b32_e32 v127, v0
	s_barrier

; #define WAIT_V(n) asm volatile("s_waitcnt vmcnt(" #n ")" ::: "memory")
; #define BAR __builtin_amdgcn_s_barrier()
; template <int N, int K, int EPI>
; __device__ __forceinline__ void gemm_phase(const bf16* __restrict__ A, const bf16* __restrict__ Bt, float* __restrict__ outf, bf16* __restrict__ outb,
;                            const float* __restrict__ ropec, const int W) {
;     ...
;   for (int vt = blockIdx.x; vt < nwg; vt += gridDim.x) {
;     int wgid = vt;
;     { int q = nwg / NXCD, r = nwg % NXCD, xcd = wgid % NXCD, off = wgid / NXCD;
;       wgid = (xcd < r ? xcd * (q + 1) : r * (q + 1) + (xcd - r) * q) + off; }
;     const int nig = WGM * nN, gid = wgid / nig, fm = gid * WGM, gsz = min(nM - fm, WGM);
;     const int pm = fm + ((wgid % nig) % gsz), pn = (wgid % nig) / gsz, brow = pm * BM, bcol = pn * BM;
;     f32x4 acc[2][2][4][2] = {};
;     bf16x8 At[4][2], B0[2][2], B1[2][2];
;     STAGE(SB(0, 0), Bt, bcol, 0); STAGE(SA(0, 0), A, brow, 0);
;     STAGE(SB(0, 1), Bt, bcol + HALF, 0); STAGE(SA(0, 1), A, brow + HALF, 0);
;     if (wr == 1) BAR;
;     WAIT_V(4); BAR;
;     STAGE(SB(1, 0), Bt, bcol, 1); STAGE(SA(1, 0), A, brow, 1); STAGE(SB(1, 1), Bt, bcol + HALF, 1);
;     WAIT_V(6); BAR;
.LBB0_192:
	s_ashr_i32 s6, s80, 3
	s_add_i32 s6, s84, s6
	s_ashr_i32 s7, s6, 31
	s_lshr_b32 s7, s7, 25
	s_add_i32 s7, s6, s7
	s_and_b32 s80, s7, 0xff80
	s_sub_i32 s6, s6, s80
	s_bfe_i32 s80, s6, 0x80000
	s_bfe_u32 s80, s80, 0x3000c
	s_add_i32 s80, s6, s80
	s_bfe_i32 s81, s80, 0x80000
	s_and_b32 s80, s80, 0xf8
	s_sub_i32 s6, s6, s80
	s_sext_i32_i8 s6, s6
	s_lshl_b32 s7, s7, 4
	s_sext_i32_i16 s81, s81
	s_and_b32 s7, s7, 0xfffff800
	s_lshl_b32 s6, s6, 8
	s_add_i32 s96, s6, s7
	s_lshl_b32 s6, s81, 5
	s_and_b32 s94, s6, 0xffffff00
	s_ashr_i32 s95, s94, 31
	s_lshl_b64 s[80:81], s[94:95], 11
	s_add_u32 s6, s88, s80
	s_addc_u32 s7, s89, s81
	v_lshl_add_u64 v[0:1], s[6:7], 0, v[128:129]
	v_readfirstlane_b32 s6, v134
	s_mov_b32 m0, s6
	v_readfirstlane_b32 s6, v135
	s_ashr_i32 s97, s96, 31
	global_load_lds_dwordx4 v[0:1], off
	s_mov_b32 m0, s6
	s_lshl_b64 s[6:7], s[96:97], 11
	s_add_u32 s84, s56, s6
	v_lshl_add_u64 v[2:3], v[0:1], 0, s[8:9]
	s_addc_u32 s85, s57, s7
	global_load_lds_dwordx4 v[2:3], off
	v_lshl_add_u64 v[2:3], s[84:85], 0, v[128:129]
	v_readfirstlane_b32 s84, v136
	s_mov_b32 m0, s84
	v_readfirstlane_b32 s84, v137
	global_load_lds_dwordx4 v[2:3], off
	s_mov_b32 m0, s84
	s_or_b32 s84, s94, 0x80
	s_ashr_i32 s85, s84, 31
	s_lshl_b64 s[84:85], s[84:85], 11
	s_add_u32 s84, s88, s84
	v_lshl_add_u64 v[4:5], v[2:3], 0, s[8:9]
	s_addc_u32 s85, s89, s85
	global_load_lds_dwordx4 v[4:5], off
	v_lshl_add_u64 v[4:5], s[84:85], 0, v[128:129]
	v_readfirstlane_b32 s84, v138
	s_mov_b32 m0, s84
	v_readfirstlane_b32 s84, v139
	global_load_lds_dwordx4 v[4:5], off
	s_mov_b32 m0, s84
	s_or_b32 s84, s96, 0x80
	s_ashr_i32 s85, s84, 31
	s_lshl_b64 s[84:85], s[84:85], 11
	s_add_u32 s84, s56, s84
	s_addc_u32 s85, s57, s85
	v_lshl_add_u64 v[6:7], v[4:5], 0, s[8:9]
	v_lshl_add_u64 v[132:133], s[84:85], 0, v[128:129]
	v_readfirstlane_b32 s84, v140
	global_load_lds_dwordx4 v[6:7], off
	s_mov_b32 m0, s84
	v_readfirstlane_b32 s84, v141
	global_load_lds_dwordx4 v[132:133], off
	v_lshl_add_u64 v[6:7], v[132:133], 0, s[8:9]
	s_mov_b32 m0, s84
	s_and_b64 vcc, exec, s[0:1]
	global_load_lds_dwordx4 v[6:7], off
	v_readfirstlane_b32 s84, v154
	v_lshl_add_u64 v[6:7], v[0:1], 0, s[86:87]
	s_mov_b32 m0, s84
	v_readfirstlane_b32 s84, v155
	global_load_lds_dwordx4 v[6:7], off
	v_lshl_add_u64 v[0:1], v[0:1], 0, s[92:93]
	s_mov_b32 m0, s84
	v_readfirstlane_b32 s84, v142
	global_load_lds_dwordx4 v[0:1], off
	v_lshl_add_u64 v[0:1], v[2:3], 0, s[86:87]
	s_mov_b32 m0, s84
	v_readfirstlane_b32 s84, v143
	global_load_lds_dwordx4 v[0:1], off
	v_lshl_add_u64 v[0:1], v[2:3], 0, s[92:93]
	s_mov_b32 m0, s84
	v_readfirstlane_b32 s84, v156
	global_load_lds_dwordx4 v[0:1], off
	v_lshl_add_u64 v[0:1], v[4:5], 0, s[86:87]
	s_mov_b32 m0, s84
	v_readfirstlane_b32 s84, v157
	global_load_lds_dwordx4 v[0:1], off
	v_lshl_add_u64 v[0:1], v[4:5], 0, s[92:93]
	s_mov_b32 m0, s84
	s_add_u32 s80, s52, s80
	global_load_lds_dwordx4 v[0:1], off
	s_cbranch_vccnz .LBB0_194
	s_barrier
.LBB0_194:
	s_waitcnt vmcnt(10)
	s_barrier
	s_waitcnt vmcnt(6)
	s_addc_u32 s81, s53, s81
	s_add_u32 s84, s52, s6
	v_mov_b32_e32 v0, 0
	s_addc_u32 s85, s53, s7
	s_mov_b32 s6, -2
	v_mov_b32_e32 v1, v0
	v_mov_b32_e32 v2, v0
	v_mov_b32_e32 v3, v0
	v_mov_b32_e32 v4, v0
	v_mov_b32_e32 v5, v0
	v_mov_b32_e32 v6, v0
	v_mov_b32_e32 v7, v0
	v_mov_b32_e32 v8, v0
	v_mov_b32_e32 v9, v0
	v_mov_b32_e32 v10, v0
	v_mov_b32_e32 v11, v0
	v_mov_b32_e32 v12, v0
	v_mov_b32_e32 v13, v0
	v_mov_b32_e32 v14, v0
	v_mov_b32_e32 v15, v0
	v_mov_b32_e32 v16, v0
	v_mov_b32_e32 v17, v0
	v_mov_b32_e32 v18, v0
	v_mov_b32_e32 v19, v0
	v_mov_b32_e32 v20, v0
	v_mov_b32_e32 v21, v0
	v_mov_b32_e32 v22, v0
	v_mov_b32_e32 v23, v0
	v_mov_b32_e32 v24, v0
	v_mov_b32_e32 v25, v0
	v_mov_b32_e32 v26, v0
	v_mov_b32_e32 v27, v0
	v_mov_b32_e32 v28, v0
	v_mov_b32_e32 v29, v0
	v_mov_b32_e32 v30, v0
	v_mov_b32_e32 v31, v0
	v_mov_b32_e32 v32, v0
	v_mov_b32_e32 v33, v0
	v_mov_b32_e32 v34, v0
	v_mov_b32_e32 v35, v0
	v_mov_b32_e32 v36, v0
	v_mov_b32_e32 v37, v0
	v_mov_b32_e32 v38, v0
	v_mov_b32_e32 v39, v0
	v_mov_b32_e32 v40, v0
	v_mov_b32_e32 v41, v0
	v_mov_b32_e32 v42, v0
	v_mov_b32_e32 v43, v0
	v_mov_b32_e32 v44, v0
	v_mov_b32_e32 v45, v0
	v_mov_b32_e32 v46, v0
	v_mov_b32_e32 v47, v0
	v_mov_b32_e32 v48, v0
	v_mov_b32_e32 v49, v0
	v_mov_b32_e32 v50, v0
	v_mov_b32_e32 v51, v0
	v_mov_b32_e32 v52, v0
	v_mov_b32_e32 v53, v0
	v_mov_b32_e32 v54, v0
	v_mov_b32_e32 v55, v0
	v_mov_b32_e32 v56, v0
	v_mov_b32_e32 v57, v0
	v_mov_b32_e32 v58, v0
	v_mov_b32_e32 v59, v0
	v_mov_b32_e32 v60, v0
	v_mov_b32_e32 v61, v0
	v_mov_b32_e32 v62, v0
	v_mov_b32_e32 v63, v0
	v_mov_b32_e32 v64, v0
	v_mov_b32_e32 v65, v0
	v_mov_b32_e32 v66, v0
	v_mov_b32_e32 v67, v0
	v_mov_b32_e32 v68, v0
	v_mov_b32_e32 v69, v0
	v_mov_b32_e32 v70, v0
	v_mov_b32_e32 v71, v0
	v_mov_b32_e32 v72, v0
	v_mov_b32_e32 v73, v0
	v_mov_b32_e32 v74, v0
	v_mov_b32_e32 v75, v0
	v_mov_b32_e32 v76, v0
	v_mov_b32_e32 v77, v0
	v_mov_b32_e32 v78, v0
	v_mov_b32_e32 v79, v0
	v_mov_b32_e32 v80, v0
	v_mov_b32_e32 v81, v0
	v_mov_b32_e32 v82, v0
	v_mov_b32_e32 v83, v0
	v_mov_b32_e32 v84, v0
	v_mov_b32_e32 v85, v0
	v_mov_b32_e32 v86, v0
	v_mov_b32_e32 v87, v0
	v_mov_b32_e32 v88, v0
	v_mov_b32_e32 v89, v0
	v_mov_b32_e32 v90, v0
	v_mov_b32_e32 v91, v0
	v_mov_b32_e32 v92, v0
	v_mov_b32_e32 v93, v0
	v_mov_b32_e32 v94, v0
	v_mov_b32_e32 v95, v0
	v_mov_b32_e32 v96, v0
	v_mov_b32_e32 v97, v0
	v_mov_b32_e32 v98, v0
	v_mov_b32_e32 v99, v0
	v_mov_b32_e32 v100, v0
	v_mov_b32_e32 v101, v0
	v_mov_b32_e32 v102, v0
	v_mov_b32_e32 v103, v0
	v_mov_b32_e32 v104, v0
	v_mov_b32_e32 v105, v0
	v_mov_b32_e32 v106, v0
	v_mov_b32_e32 v107, v0
	v_mov_b32_e32 v108, v0
	v_mov_b32_e32 v109, v0
	v_mov_b32_e32 v110, v0
	v_mov_b32_e32 v111, v0
	v_mov_b32_e32 v112, v0
	v_mov_b32_e32 v113, v0
	v_mov_b32_e32 v114, v0
	v_mov_b32_e32 v115, v0
	v_mov_b32_e32 v116, v0
	v_mov_b32_e32 v117, v0
	v_mov_b32_e32 v118, v0
	v_mov_b32_e32 v119, v0
	v_mov_b32_e32 v120, v0
	v_mov_b32_e32 v121, v0
	v_mov_b32_e32 v122, v0
	v_mov_b32_e32 v123, v0
	v_mov_b32_e32 v124, v0
	v_mov_b32_e32 v125, v0
	v_mov_b32_e32 v126, v0
	v_mov_b32_e32 v127, v0
	s_barrier

; #define WAIT_V(n) asm volatile("s_waitcnt vmcnt(" #n ")" ::: "memory")
; #define BAR __builtin_amdgcn_s_barrier()
; template <int N, int K, int EPI>
; __device__ __forceinline__ void gemm_phase(const bf16* __restrict__ A, const bf16* __restrict__ Bt, float* __restrict__ outf, bf16* __restrict__ outb,
;                            const float* __restrict__ ropec, const int W) {
;     ...
;     f32x4 acc[2][2][4][2] = {};
;     bf16x8 At[4][2], B0[2][2], B1[2][2];
;     STAGE(SB(0, 0), Bt, bcol, 0); STAGE(SA(0, 0), A, brow, 0);
;     STAGE(SB(0, 1), Bt, bcol + HALF, 0); STAGE(SA(0, 1), A, brow + HALF, 0);
;     if (wr == 1) BAR;
;     WAIT_V(4); BAR;
;     STAGE(SB(1, 0), Bt, bcol, 1); STAGE(SA(1, 0), A, brow, 1); STAGE(SB(1, 1), Bt, bcol + HALF, 1);
;     WAIT_V(6); BAR;
.LBB0_215:
	v_readfirstlane_b32 s8, v154
	v_lshl_add_u64 v[6:7], v[0:1], 0, s[92:93]
	s_mov_b32 m0, s8
	v_readfirstlane_b32 s8, v155
	s_waitcnt vmcnt(4)
	s_barrier
	global_load_lds_dwordx4 v[6:7], off
	v_lshl_add_u64 v[0:1], v[0:1], 0, s[94:95]
	s_mov_b32 m0, s8
	v_readfirstlane_b32 s8, v142
	global_load_lds_dwordx4 v[0:1], off
	v_lshl_add_u64 v[0:1], v[2:3], 0, s[92:93]
	s_mov_b32 m0, s8
	v_readfirstlane_b32 s8, v143
	global_load_lds_dwordx4 v[0:1], off
	v_lshl_add_u64 v[0:1], v[2:3], 0, s[94:95]
	s_mov_b32 m0, s8
	v_readfirstlane_b32 s8, v156
	global_load_lds_dwordx4 v[0:1], off
	v_lshl_add_u64 v[0:1], v[4:5], 0, s[92:93]
	s_mov_b32 m0, s8
	v_readfirstlane_b32 s8, v157
	global_load_lds_dwordx4 v[0:1], off
	v_lshl_add_u64 v[0:1], v[4:5], 0, s[94:95]
	s_mov_b32 m0, s8
	s_add_u32 vcc_lo, s52, s84
	global_load_lds_dwordx4 v[0:1], off
	s_waitcnt vmcnt(6)
	s_addc_u32 vcc_hi, s53, s85
	s_add_u32 s84, s52, s6
	v_mov_b32_e32 v0, 0
	s_addc_u32 s85, s53, s7
	s_mov_b32 s6, -2
	v_mov_b32_e32 v1, v0
	v_mov_b32_e32 v2, v0
	v_mov_b32_e32 v3, v0
	v_mov_b32_e32 v4, v0
	v_mov_b32_e32 v5, v0
	v_mov_b32_e32 v6, v0
	v_mov_b32_e32 v7, v0
	v_mov_b32_e32 v8, v0
	v_mov_b32_e32 v9, v0
	v_mov_b32_e32 v10, v0
	v_mov_b32_e32 v11, v0
	v_mov_b32_e32 v12, v0
	v_mov_b32_e32 v13, v0
	v_mov_b32_e32 v14, v0
	v_mov_b32_e32 v15, v0
	v_mov_b32_e32 v16, v0
	v_mov_b32_e32 v17, v0
	v_mov_b32_e32 v18, v0
	v_mov_b32_e32 v19, v0
	v_mov_b32_e32 v20, v0
	v_mov_b32_e32 v21, v0
	v_mov_b32_e32 v22, v0
	v_mov_b32_e32 v23, v0
	v_mov_b32_e32 v24, v0
	v_mov_b32_e32 v25, v0
	v_mov_b32_e32 v26, v0
	v_mov_b32_e32 v27, v0
	v_mov_b32_e32 v28, v0
	v_mov_b32_e32 v29, v0
	v_mov_b32_e32 v30, v0
	v_mov_b32_e32 v31, v0
	v_mov_b32_e32 v32, v0
	v_mov_b32_e32 v33, v0
	v_mov_b32_e32 v34, v0
	v_mov_b32_e32 v35, v0
	v_mov_b32_e32 v36, v0
	v_mov_b32_e32 v37, v0
	v_mov_b32_e32 v38, v0
	v_mov_b32_e32 v39, v0
	v_mov_b32_e32 v40, v0
	v_mov_b32_e32 v41, v0
	v_mov_b32_e32 v42, v0
	v_mov_b32_e32 v43, v0
	v_mov_b32_e32 v44, v0
	v_mov_b32_e32 v45, v0
	v_mov_b32_e32 v46, v0
	v_mov_b32_e32 v47, v0
	v_mov_b32_e32 v48, v0
	v_mov_b32_e32 v49, v0
	v_mov_b32_e32 v50, v0
	v_mov_b32_e32 v51, v0
	v_mov_b32_e32 v52, v0
	v_mov_b32_e32 v53, v0
	v_mov_b32_e32 v54, v0
	v_mov_b32_e32 v55, v0
	v_mov_b32_e32 v56, v0
	v_mov_b32_e32 v57, v0
	v_mov_b32_e32 v58, v0
	v_mov_b32_e32 v59, v0
	v_mov_b32_e32 v60, v0
	v_mov_b32_e32 v61, v0
	v_mov_b32_e32 v62, v0
	v_mov_b32_e32 v63, v0
	v_mov_b32_e32 v64, v0
	v_mov_b32_e32 v65, v0
	v_mov_b32_e32 v66, v0
	v_mov_b32_e32 v67, v0
	v_mov_b32_e32 v68, v0
	v_mov_b32_e32 v69, v0
	v_mov_b32_e32 v70, v0
	v_mov_b32_e32 v71, v0
	v_mov_b32_e32 v72, v0
	v_mov_b32_e32 v73, v0
	v_mov_b32_e32 v74, v0
	v_mov_b32_e32 v75, v0
	v_mov_b32_e32 v76, v0
	v_mov_b32_e32 v77, v0
	v_mov_b32_e32 v78, v0
	v_mov_b32_e32 v79, v0
	v_mov_b32_e32 v80, v0
	v_mov_b32_e32 v81, v0
	v_mov_b32_e32 v82, v0
	v_mov_b32_e32 v83, v0
	v_mov_b32_e32 v84, v0
	v_mov_b32_e32 v85, v0
	v_mov_b32_e32 v86, v0
	v_mov_b32_e32 v87, v0
	v_mov_b32_e32 v88, v0
	v_mov_b32_e32 v89, v0
	v_mov_b32_e32 v90, v0
	v_mov_b32_e32 v91, v0
	v_mov_b32_e32 v92, v0
	v_mov_b32_e32 v93, v0
	v_mov_b32_e32 v94, v0
	v_mov_b32_e32 v95, v0
	v_mov_b32_e32 v96, v0
	v_mov_b32_e32 v97, v0
	v_mov_b32_e32 v98, v0
	v_mov_b32_e32 v99, v0
	v_mov_b32_e32 v100, v0
	v_mov_b32_e32 v101, v0
	v_mov_b32_e32 v102, v0
	v_mov_b32_e32 v103, v0
	v_mov_b32_e32 v104, v0
	v_mov_b32_e32 v105, v0
	v_mov_b32_e32 v106, v0
	v_mov_b32_e32 v107, v0
	v_mov_b32_e32 v108, v0
	v_mov_b32_e32 v109, v0
	v_mov_b32_e32 v110, v0
	v_mov_b32_e32 v111, v0
	v_mov_b32_e32 v112, v0
	v_mov_b32_e32 v113, v0
	v_mov_b32_e32 v114, v0
	v_mov_b32_e32 v115, v0
	v_mov_b32_e32 v116, v0
	v_mov_b32_e32 v117, v0
	v_mov_b32_e32 v118, v0
	v_mov_b32_e32 v119, v0
	v_mov_b32_e32 v120, v0
	v_mov_b32_e32 v121, v0
	v_mov_b32_e32 v122, v0
	v_mov_b32_e32 v123, v0
	v_mov_b32_e32 v124, v0
	v_mov_b32_e32 v125, v0
	v_mov_b32_e32 v126, v0
	v_mov_b32_e32 v127, v0
	s_barrier

; #define WAIT_V(n) asm volatile("s_waitcnt vmcnt(" #n ")" ::: "memory")
; #define BAR __builtin_amdgcn_s_barrier()
; template <int N, int K, int EPI>
; __device__ __forceinline__ void gemm_phase(const bf16* __restrict__ A, const bf16* __restrict__ Bt, float* __restrict__ outf, bf16* __restrict__ outb,
;                            const float* __restrict__ ropec, const int W) {
;     ...
;   for (int vt = blockIdx.x; vt < nwg; vt += gridDim.x) {
;     int wgid = vt;
;     { int q = nwg / NXCD, r = nwg % NXCD, xcd = wgid % NXCD, off = wgid / NXCD;
;       wgid = (xcd < r ? xcd * (q + 1) : r * (q + 1) + (xcd - r) * q) + off; }
;     const int nig = WGM * nN, gid = wgid / nig, fm = gid * WGM, gsz = min(nM - fm, WGM);
;     const int pm = fm + ((wgid % nig) % gsz), pn = (wgid % nig) / gsz, brow = pm * BM, bcol = pn * BM;
;     f32x4 acc[2][2][4][2] = {};
;     bf16x8 At[4][2], B0[2][2], B1[2][2];
;     STAGE(SB(0, 0), Bt, bcol, 0); STAGE(SA(0, 0), A, brow, 0);
;     STAGE(SB(0, 1), Bt, bcol + HALF, 0); STAGE(SA(0, 1), A, brow + HALF, 0);
;     if (wr == 1) BAR;
;     WAIT_V(4); BAR;
;     STAGE(SB(1, 0), Bt, bcol, 1); STAGE(SA(1, 0), A, brow, 1); STAGE(SB(1, 1), Bt, bcol + HALF, 1);
;     WAIT_V(6); BAR;
.LBB0_261:
	s_ashr_i32 s6, s90, 31
	s_lshr_b32 s6, s6, 29
	s_add_i32 s6, s90, s6
	s_ashr_i32 s7, s6, 3
	s_and_b32 s6, s6, -8
	s_sub_i32 s6, s90, s6
	s_cmp_lt_i32 s6, 0
	s_movk_i32 s8, 0xc1
	s_cselect_b32 s8, s8, 0xc0
	s_mul_i32 s6, s8, s6
	s_add_i32 s6, s6, s7
	s_mul_hi_i32 s7, s6, 0x2aaaaaab
	s_lshr_b32 s8, s7, 31
	s_ashr_i32 s7, s7, 4
	s_add_i32 s7, s7, s8
	s_lshl_b32 s92, s7, 3
	s_mulk_i32 s7, 0x60
	s_sub_i32 s91, s6, s7
	s_bfe_i32 s6, s91, 0x80000
	s_bfe_u32 s6, s6, 0x3000c
	s_add_i32 s6, s91, s6
	s_bfe_i32 s7, s6, 0x80000
	s_sext_i32_i16 s7, s7
	s_and_b32 s6, s6, 0xf8
	s_lshr_b32 s93, s7, 3
	s_sub_i32 s6, s91, s6
	s_sext_i32_i8 s6, s6
	s_lshl_b32 s40, s93, 8
	s_add_i32 s92, s92, s6
	s_ashr_i32 s41, s40, 31
	s_lshl_b32 s42, s92, 8
	s_lshl_b64 s[6:7], s[40:41], 11
	s_add_u32 s10, s52, s6
	s_addc_u32 s11, s53, s7
	v_readfirstlane_b32 s6, v148
	v_lshl_add_u64 v[0:1], s[10:11], 0, v[142:143]
	s_mov_b32 m0, s6
	v_readfirstlane_b32 s6, v149
	s_ashr_i32 s43, s42, 31
	global_load_lds_dwordx4 v[0:1], off
	s_mov_b32 m0, s6
	s_lshl_b64 s[6:7], s[42:43], 11
	s_add_u32 s8, s56, s6
	v_lshl_add_u64 v[2:3], v[0:1], 0, s[20:21]
	s_addc_u32 s9, s57, s7
	global_load_lds_dwordx4 v[2:3], off
	v_lshl_add_u64 v[2:3], s[8:9], 0, v[142:143]
	v_readfirstlane_b32 s8, v150
	s_mov_b32 m0, s8
	v_readfirstlane_b32 s8, v151
	global_load_lds_dwordx4 v[2:3], off
	s_mov_b32 m0, s8
	s_or_b32 s8, s40, 0x80
	s_ashr_i32 s9, s8, 31
	s_lshl_b64 s[8:9], s[8:9], 11
	s_add_u32 s8, s52, s8
	v_lshl_add_u64 v[4:5], v[2:3], 0, s[20:21]
	s_addc_u32 s9, s53, s9
	global_load_lds_dwordx4 v[4:5], off
	v_lshl_add_u64 v[4:5], s[8:9], 0, v[142:143]
	v_readfirstlane_b32 s8, v152
	s_mov_b32 m0, s8
	v_readfirstlane_b32 s8, v153
	global_load_lds_dwordx4 v[4:5], off
	s_mov_b32 m0, s8
	s_or_b32 s8, s42, 0x80
	s_ashr_i32 s9, s8, 31
	s_lshl_b64 s[8:9], s[8:9], 11
	s_add_u32 s8, s56, s8
	s_addc_u32 s9, s57, s9
	v_lshl_add_u64 v[6:7], v[4:5], 0, s[20:21]
	v_lshl_add_u64 v[128:129], s[8:9], 0, v[142:143]
	v_readfirstlane_b32 s8, v154
	global_load_lds_dwordx4 v[6:7], off
	s_mov_b32 m0, s8
	v_readfirstlane_b32 s8, v155
	global_load_lds_dwordx4 v[128:129], off
	v_lshl_add_u64 v[6:7], v[128:129], 0, s[20:21]
	s_mov_b32 m0, s8
	s_and_b64 vcc, exec, s[0:1]
	global_load_lds_dwordx4 v[6:7], off
	v_readfirstlane_b32 s8, v168
	v_lshl_add_u64 v[6:7], v[0:1], 0, s[24:25]
	s_mov_b32 m0, s8
	v_readfirstlane_b32 s8, v169
	global_load_lds_dwordx4 v[6:7], off
	v_lshl_add_u64 v[0:1], v[0:1], 0, s[26:27]
	s_mov_b32 m0, s8
	v_readfirstlane_b32 s8, v156
	global_load_lds_dwordx4 v[0:1], off
	v_lshl_add_u64 v[0:1], v[2:3], 0, s[24:25]
	s_mov_b32 m0, s8
	v_readfirstlane_b32 s8, v157
	global_load_lds_dwordx4 v[0:1], off
	v_lshl_add_u64 v[0:1], v[2:3], 0, s[26:27]
	s_mov_b32 m0, s8
	v_readfirstlane_b32 s8, v170
	global_load_lds_dwordx4 v[0:1], off
	v_lshl_add_u64 v[0:1], v[4:5], 0, s[24:25]
	s_mov_b32 m0, s8
	v_readfirstlane_b32 s8, v171
	global_load_lds_dwordx4 v[0:1], off
	v_lshl_add_u64 v[0:1], v[4:5], 0, s[26:27]
	s_mov_b32 m0, s8
	s_add_u32 s80, s52, s6
	global_load_lds_dwordx4 v[0:1], off
	s_cbranch_vccnz .LBB0_263
	s_barrier
.LBB0_263:
	s_waitcnt vmcnt(10)
	s_barrier
	s_waitcnt vmcnt(6)
	v_mov_b32_e32 v0, 0
	s_addc_u32 s81, s53, s7
	s_mov_b32 s6, -2
	v_mov_b32_e32 v1, v0
	v_mov_b32_e32 v2, v0
	v_mov_b32_e32 v3, v0
	v_mov_b32_e32 v4, v0
	v_mov_b32_e32 v5, v0
	v_mov_b32_e32 v6, v0
	v_mov_b32_e32 v7, v0
	v_mov_b32_e32 v8, v0
	v_mov_b32_e32 v9, v0
	v_mov_b32_e32 v10, v0
	v_mov_b32_e32 v11, v0
	v_mov_b32_e32 v12, v0
	v_mov_b32_e32 v13, v0
	v_mov_b32_e32 v14, v0
	v_mov_b32_e32 v15, v0
	v_mov_b32_e32 v16, v0
	v_mov_b32_e32 v17, v0
	v_mov_b32_e32 v18, v0
	v_mov_b32_e32 v19, v0
	v_mov_b32_e32 v20, v0
	v_mov_b32_e32 v21, v0
	v_mov_b32_e32 v22, v0
	v_mov_b32_e32 v23, v0
	v_mov_b32_e32 v24, v0
	v_mov_b32_e32 v25, v0
	v_mov_b32_e32 v26, v0
	v_mov_b32_e32 v27, v0
	v_mov_b32_e32 v28, v0
	v_mov_b32_e32 v29, v0
	v_mov_b32_e32 v30, v0
	v_mov_b32_e32 v31, v0
	v_mov_b32_e32 v32, v0
	v_mov_b32_e32 v33, v0
	v_mov_b32_e32 v34, v0
	v_mov_b32_e32 v35, v0
	v_mov_b32_e32 v36, v0
	v_mov_b32_e32 v37, v0
	v_mov_b32_e32 v38, v0
	v_mov_b32_e32 v39, v0
	v_mov_b32_e32 v40, v0
	v_mov_b32_e32 v41, v0
	v_mov_b32_e32 v42, v0
	v_mov_b32_e32 v43, v0
	v_mov_b32_e32 v44, v0
	v_mov_b32_e32 v45, v0
	v_mov_b32_e32 v46, v0
	v_mov_b32_e32 v47, v0
	v_mov_b32_e32 v48, v0
	v_mov_b32_e32 v49, v0
	v_mov_b32_e32 v50, v0
	v_mov_b32_e32 v51, v0
	v_mov_b32_e32 v52, v0
	v_mov_b32_e32 v53, v0
	v_mov_b32_e32 v54, v0
	v_mov_b32_e32 v55, v0
	v_mov_b32_e32 v56, v0
	v_mov_b32_e32 v57, v0
	v_mov_b32_e32 v58, v0
	v_mov_b32_e32 v59, v0
	v_mov_b32_e32 v60, v0
	v_mov_b32_e32 v61, v0
	v_mov_b32_e32 v62, v0
	v_mov_b32_e32 v63, v0
	v_mov_b32_e32 v64, v0
	v_mov_b32_e32 v65, v0
	v_mov_b32_e32 v66, v0
	v_mov_b32_e32 v67, v0
	v_mov_b32_e32 v68, v0
	v_mov_b32_e32 v69, v0
	v_mov_b32_e32 v70, v0
	v_mov_b32_e32 v71, v0
	v_mov_b32_e32 v72, v0
	v_mov_b32_e32 v73, v0
	v_mov_b32_e32 v74, v0
	v_mov_b32_e32 v75, v0
	v_mov_b32_e32 v76, v0
	v_mov_b32_e32 v77, v0
	v_mov_b32_e32 v78, v0
	v_mov_b32_e32 v79, v0
	v_mov_b32_e32 v80, v0
	v_mov_b32_e32 v81, v0
	v_mov_b32_e32 v82, v0
	v_mov_b32_e32 v83, v0
	v_mov_b32_e32 v84, v0
	v_mov_b32_e32 v85, v0
	v_mov_b32_e32 v86, v0
	v_mov_b32_e32 v87, v0
	v_mov_b32_e32 v88, v0
	v_mov_b32_e32 v89, v0
	v_mov_b32_e32 v90, v0
	v_mov_b32_e32 v91, v0
	v_mov_b32_e32 v92, v0
	v_mov_b32_e32 v93, v0
	v_mov_b32_e32 v94, v0
	v_mov_b32_e32 v95, v0
	v_mov_b32_e32 v96, v0
	v_mov_b32_e32 v97, v0
	v_mov_b32_e32 v98, v0
	v_mov_b32_e32 v99, v0
	v_mov_b32_e32 v100, v0
	v_mov_b32_e32 v101, v0
	v_mov_b32_e32 v102, v0
	v_mov_b32_e32 v103, v0
	v_mov_b32_e32 v104, v0
	v_mov_b32_e32 v105, v0
	v_mov_b32_e32 v106, v0
	v_mov_b32_e32 v107, v0
	v_mov_b32_e32 v108, v0
	v_mov_b32_e32 v109, v0
	v_mov_b32_e32 v110, v0
	v_mov_b32_e32 v111, v0
	v_mov_b32_e32 v112, v0
	v_mov_b32_e32 v113, v0
	v_mov_b32_e32 v114, v0
	v_mov_b32_e32 v115, v0
	v_mov_b32_e32 v116, v0
	v_mov_b32_e32 v117, v0
	v_mov_b32_e32 v118, v0
	v_mov_b32_e32 v119, v0
	v_mov_b32_e32 v120, v0
	v_mov_b32_e32 v121, v0
	v_mov_b32_e32 v122, v0
	v_mov_b32_e32 v123, v0
	v_mov_b32_e32 v124, v0
	v_mov_b32_e32 v125, v0
	v_mov_b32_e32 v126, v0
	v_mov_b32_e32 v127, v0
	s_barrier

; #define WAIT_V(n) asm volatile("s_waitcnt vmcnt(" #n ")" ::: "memory")
; #define BAR __builtin_amdgcn_s_barrier()
; template <int N, int K, int EPI>
; __device__ __forceinline__ void gemm_phase(const bf16* __restrict__ A, const bf16* __restrict__ Bt, float* __restrict__ outf, bf16* __restrict__ outb,
;                            const float* __restrict__ ropec, const int W) {
;     ...
;   for (int vt = blockIdx.x; vt < nwg; vt += gridDim.x) {
;     int wgid = vt;
;     { int q = nwg / NXCD, r = nwg % NXCD, xcd = wgid % NXCD, off = wgid / NXCD;
;       wgid = (xcd < r ? xcd * (q + 1) : r * (q + 1) + (xcd - r) * q) + off; }
;     const int nig = WGM * nN, gid = wgid / nig, fm = gid * WGM, gsz = min(nM - fm, WGM);
;     const int pm = fm + ((wgid % nig) % gsz), pn = (wgid % nig) / gsz, brow = pm * BM, bcol = pn * BM;
;     f32x4 acc[2][2][4][2] = {};
;     bf16x8 At[4][2], B0[2][2], B1[2][2];
;     STAGE(SB(0, 0), Bt, bcol, 0); STAGE(SA(0, 0), A, brow, 0);
;     STAGE(SB(0, 1), Bt, bcol + HALF, 0); STAGE(SA(0, 1), A, brow + HALF, 0);
;     if (wr == 1) BAR;
;     WAIT_V(4); BAR;
;     STAGE(SB(1, 0), Bt, bcol, 1); STAGE(SA(1, 0), A, brow, 1); STAGE(SB(1, 1), Bt, bcol + HALF, 1);
;     WAIT_V(6); BAR;
.LBB0_366:
	s_ashr_i32 s8, s76, 3
	s_add_i32 s8, s80, s8
	s_ashr_i32 s9, s8, 31
	s_lshr_b32 s9, s9, 27
	s_add_i32 s9, s8, s9
	s_and_b32 s74, s9, 0xffe0
	s_sub_i32 s8, s8, s74
	s_bfe_i32 s74, s8, 0x80000
	s_bfe_u32 s74, s74, 0x3000c
	s_add_i32 s74, s8, s74
	s_bfe_i32 s75, s74, 0x80000
	s_and_b32 s74, s74, 0xf8
	s_sub_i32 s8, s8, s74
	s_sext_i32_i8 s8, s8
	s_lshl_b32 s9, s9, 6
	s_sext_i32_i16 s75, s75
	s_and_b32 s9, s9, 0xfffff800
	s_lshl_b32 s8, s8, 8
	s_add_i32 s76, s8, s9
	s_lshl_b32 s8, s75, 5
	s_and_b32 s74, s8, 0xffffff00
	s_ashr_i32 s75, s74, 31
	s_lshl_b64 s[80:81], s[74:75], 11
	s_add_u32 s8, s78, s80
	s_addc_u32 s9, s79, s81
	v_lshl_add_u64 v[0:1], s[8:9], 0, v[128:129]
	v_readfirstlane_b32 s8, v134
	s_ashr_i32 s77, s76, 31
	s_mov_b32 m0, s8
	v_readfirstlane_b32 s8, v135
	s_lshl_b64 s[82:83], s[76:77], 11
	global_load_lds_dwordx4 v[0:1], off
	s_mov_b32 m0, s8
	s_add_u32 s8, s56, s82
	v_lshl_add_u64 v[2:3], v[0:1], 0, s[6:7]
	s_addc_u32 s9, s57, s83
	global_load_lds_dwordx4 v[2:3], off
	v_lshl_add_u64 v[2:3], s[8:9], 0, v[128:129]
	v_readfirstlane_b32 s8, v136
	s_mov_b32 m0, s8
	v_readfirstlane_b32 s8, v137
	global_load_lds_dwordx4 v[2:3], off
	s_mov_b32 m0, s8
	s_or_b32 s8, s74, 0x80
	s_ashr_i32 s9, s8, 31
	s_lshl_b64 s[8:9], s[8:9], 11
	s_add_u32 s8, s78, s8
	v_lshl_add_u64 v[4:5], v[2:3], 0, s[6:7]
	s_addc_u32 s9, s79, s9
	global_load_lds_dwordx4 v[4:5], off
	v_lshl_add_u64 v[4:5], s[8:9], 0, v[128:129]
	v_readfirstlane_b32 s8, v138
	s_mov_b32 m0, s8
	v_readfirstlane_b32 s8, v139
	global_load_lds_dwordx4 v[4:5], off
	s_mov_b32 m0, s8
	s_or_b32 s8, s76, 0x80
	s_ashr_i32 s9, s8, 31
	s_lshl_b64 s[8:9], s[8:9], 11
	s_add_u32 s8, s56, s8
	s_addc_u32 s9, s57, s9
	v_lshl_add_u64 v[6:7], v[4:5], 0, s[6:7]
	v_lshl_add_u64 v[132:133], s[8:9], 0, v[128:129]
	v_readfirstlane_b32 s8, v140
	global_load_lds_dwordx4 v[6:7], off
	s_mov_b32 m0, s8
	v_readfirstlane_b32 s8, v141
	global_load_lds_dwordx4 v[132:133], off
	v_lshl_add_u64 v[6:7], v[132:133], 0, s[6:7]
	s_mov_b32 m0, s8
	s_and_b64 vcc, exec, s[0:1]
	global_load_lds_dwordx4 v[6:7], off
	v_readfirstlane_b32 s8, v154
	v_lshl_add_u64 v[6:7], v[0:1], 0, s[10:11]
	s_mov_b32 m0, s8
	v_readfirstlane_b32 s8, v155
	global_load_lds_dwordx4 v[6:7], off
	v_lshl_add_u64 v[0:1], v[0:1], 0, s[14:15]
	s_mov_b32 m0, s8
	v_readfirstlane_b32 s8, v142
	global_load_lds_dwordx4 v[0:1], off
	v_lshl_add_u64 v[0:1], v[2:3], 0, s[10:11]
	s_mov_b32 m0, s8
	v_readfirstlane_b32 s8, v143
	global_load_lds_dwordx4 v[0:1], off
	v_lshl_add_u64 v[0:1], v[2:3], 0, s[14:15]
	s_mov_b32 m0, s8
	v_readfirstlane_b32 s8, v156
	global_load_lds_dwordx4 v[0:1], off
	v_lshl_add_u64 v[0:1], v[4:5], 0, s[10:11]
	s_mov_b32 m0, s8
	v_readfirstlane_b32 s8, v157
	global_load_lds_dwordx4 v[0:1], off
	v_lshl_add_u64 v[0:1], v[4:5], 0, s[14:15]
	s_mov_b32 m0, s8
	s_lshl_b64 s[76:77], s[76:77], 10
	global_load_lds_dwordx4 v[0:1], off
	s_add_u32 s80, s52, s80
	s_cbranch_vccnz .LBB0_368
	s_barrier
.LBB0_368:
	s_waitcnt vmcnt(10)
	s_barrier
	s_waitcnt vmcnt(6)
	s_addc_u32 s81, s53, s81
	s_add_u32 s82, s52, s82
	v_mov_b32_e32 v0, 0
	s_addc_u32 s83, s53, s83
	s_mov_b32 s90, -2
	v_mov_b32_e32 v1, v0
	v_mov_b32_e32 v2, v0
	v_mov_b32_e32 v3, v0
	v_mov_b32_e32 v4, v0
	v_mov_b32_e32 v5, v0
	v_mov_b32_e32 v6, v0
	v_mov_b32_e32 v7, v0
	v_mov_b32_e32 v8, v0
	v_mov_b32_e32 v9, v0
	v_mov_b32_e32 v10, v0
	v_mov_b32_e32 v11, v0
	v_mov_b32_e32 v12, v0
	v_mov_b32_e32 v13, v0
	v_mov_b32_e32 v14, v0
	v_mov_b32_e32 v15, v0
	v_mov_b32_e32 v16, v0
	v_mov_b32_e32 v17, v0
	v_mov_b32_e32 v18, v0
	v_mov_b32_e32 v19, v0
	v_mov_b32_e32 v20, v0
	v_mov_b32_e32 v21, v0
	v_mov_b32_e32 v22, v0
	v_mov_b32_e32 v23, v0
	v_mov_b32_e32 v24, v0
	v_mov_b32_e32 v25, v0
	v_mov_b32_e32 v26, v0
	v_mov_b32_e32 v27, v0
	v_mov_b32_e32 v28, v0
	v_mov_b32_e32 v29, v0
	v_mov_b32_e32 v30, v0
	v_mov_b32_e32 v31, v0
	v_mov_b32_e32 v32, v0
	v_mov_b32_e32 v33, v0
	v_mov_b32_e32 v34, v0
	v_mov_b32_e32 v35, v0
	v_mov_b32_e32 v36, v0
	v_mov_b32_e32 v37, v0
	v_mov_b32_e32 v38, v0
	v_mov_b32_e32 v39, v0
	v_mov_b32_e32 v40, v0
	v_mov_b32_e32 v41, v0
	v_mov_b32_e32 v42, v0
	v_mov_b32_e32 v43, v0
	v_mov_b32_e32 v44, v0
	v_mov_b32_e32 v45, v0
	v_mov_b32_e32 v46, v0
	v_mov_b32_e32 v47, v0
	v_mov_b32_e32 v48, v0
	v_mov_b32_e32 v49, v0
	v_mov_b32_e32 v50, v0
	v_mov_b32_e32 v51, v0
	v_mov_b32_e32 v52, v0
	v_mov_b32_e32 v53, v0
	v_mov_b32_e32 v54, v0
	v_mov_b32_e32 v55, v0
	v_mov_b32_e32 v56, v0
	v_mov_b32_e32 v57, v0
	v_mov_b32_e32 v58, v0
	v_mov_b32_e32 v59, v0
	v_mov_b32_e32 v60, v0
	v_mov_b32_e32 v61, v0
	v_mov_b32_e32 v62, v0
	v_mov_b32_e32 v63, v0
	v_mov_b32_e32 v64, v0
	v_mov_b32_e32 v65, v0
	v_mov_b32_e32 v66, v0
	v_mov_b32_e32 v67, v0
	v_mov_b32_e32 v68, v0
	v_mov_b32_e32 v69, v0
	v_mov_b32_e32 v70, v0
	v_mov_b32_e32 v71, v0
	v_mov_b32_e32 v72, v0
	v_mov_b32_e32 v73, v0
	v_mov_b32_e32 v74, v0
	v_mov_b32_e32 v75, v0
	v_mov_b32_e32 v76, v0
	v_mov_b32_e32 v77, v0
	v_mov_b32_e32 v78, v0
	v_mov_b32_e32 v79, v0
	v_mov_b32_e32 v80, v0
	v_mov_b32_e32 v81, v0
	v_mov_b32_e32 v82, v0
	v_mov_b32_e32 v83, v0
	v_mov_b32_e32 v84, v0
	v_mov_b32_e32 v85, v0
	v_mov_b32_e32 v86, v0
	v_mov_b32_e32 v87, v0
	v_mov_b32_e32 v88, v0
	v_mov_b32_e32 v89, v0
	v_mov_b32_e32 v90, v0
	v_mov_b32_e32 v91, v0
	v_mov_b32_e32 v92, v0
	v_mov_b32_e32 v93, v0
	v_mov_b32_e32 v94, v0
	v_mov_b32_e32 v95, v0
	v_mov_b32_e32 v96, v0
	v_mov_b32_e32 v97, v0
	v_mov_b32_e32 v98, v0
	v_mov_b32_e32 v99, v0
	v_mov_b32_e32 v100, v0
	v_mov_b32_e32 v101, v0
	v_mov_b32_e32 v102, v0
	v_mov_b32_e32 v103, v0
	v_mov_b32_e32 v104, v0
	v_mov_b32_e32 v105, v0
	v_mov_b32_e32 v106, v0
	v_mov_b32_e32 v107, v0
	v_mov_b32_e32 v108, v0
	v_mov_b32_e32 v109, v0
	v_mov_b32_e32 v110, v0
	v_mov_b32_e32 v111, v0
	v_mov_b32_e32 v112, v0
	v_mov_b32_e32 v113, v0
	v_mov_b32_e32 v114, v0
	v_mov_b32_e32 v115, v0
	v_mov_b32_e32 v116, v0
	v_mov_b32_e32 v117, v0
	v_mov_b32_e32 v118, v0
	v_mov_b32_e32 v119, v0
	v_mov_b32_e32 v120, v0
	v_mov_b32_e32 v121, v0
	v_mov_b32_e32 v122, v0
	v_mov_b32_e32 v123, v0
	v_mov_b32_e32 v124, v0
	v_mov_b32_e32 v125, v0
	v_mov_b32_e32 v126, v0
	v_mov_b32_e32 v127, v0
	s_barrier

; #define WAIT_V(n) asm volatile("s_waitcnt vmcnt(" #n ")" ::: "memory")
; #define BAR __builtin_amdgcn_s_barrier()
; template <int N, int K, int EPI>
; __device__ __forceinline__ void gemm_phase(const bf16* __restrict__ A, const bf16* __restrict__ Bt, float* __restrict__ outf, bf16* __restrict__ outb,
;                            const float* __restrict__ ropec, const int W) {
;     ...
;   for (int vt = blockIdx.x; vt < nwg; vt += gridDim.x) {
;     int wgid = vt;
;     { int q = nwg / NXCD, r = nwg % NXCD, xcd = wgid % NXCD, off = wgid / NXCD;
;       wgid = (xcd < r ? xcd * (q + 1) : r * (q + 1) + (xcd - r) * q) + off; }
;     const int nig = WGM * nN, gid = wgid / nig, fm = gid * WGM, gsz = min(nM - fm, WGM);
;     const int pm = fm + ((wgid % nig) % gsz), pn = (wgid % nig) / gsz, brow = pm * BM, bcol = pn * BM;
;     f32x4 acc[2][2][4][2] = {};
;     bf16x8 At[4][2], B0[2][2], B1[2][2];
;     STAGE(SB(0, 0), Bt, bcol, 0); STAGE(SA(0, 0), A, brow, 0);
;     STAGE(SB(0, 1), Bt, bcol + HALF, 0); STAGE(SA(0, 1), A, brow + HALF, 0);
;     if (wr == 1) BAR;
;     WAIT_V(4); BAR;
;     STAGE(SB(1, 0), Bt, bcol, 1); STAGE(SA(1, 0), A, brow, 1); STAGE(SB(1, 1), Bt, bcol + HALF, 1);
;     WAIT_V(6); BAR;
.LBB0_402:
	s_ashr_i32 s8, s59, 3
	s_add_i32 s8, s77, s8
	s_ashr_i32 s9, s8, 31
	s_lshr_b32 s9, s9, 25
	s_add_i32 s9, s8, s9
	s_and_b32 s59, s9, 0xff80
	s_sub_i32 s8, s8, s59
	s_bfe_i32 s59, s8, 0x80000
	s_bfe_u32 s59, s59, 0x3000c
	s_add_i32 s59, s8, s59
	s_bfe_i32 s74, s59, 0x80000
	s_and_b32 s59, s59, 0xf8
	s_sub_i32 s8, s8, s59
	s_sext_i32_i8 s8, s8
	s_lshl_b32 s9, s9, 4
	s_sext_i32_i16 s74, s74
	s_and_b32 s9, s9, 0xfffff800
	s_lshl_b32 s8, s8, 8
	s_add_i32 s76, s8, s9
	s_lshl_b32 s8, s74, 5
	s_and_b32 s74, s8, 0xffffff00
	s_ashr_i32 s75, s74, 31
	s_lshl_b64 s[78:79], s[74:75], 11
	s_add_u32 s8, s88, s78
	s_addc_u32 s9, s89, s79
	v_lshl_add_u64 v[0:1], s[8:9], 0, v[128:129]
	v_readfirstlane_b32 s8, v134
	s_ashr_i32 s77, s76, 31
	s_mov_b32 m0, s8
	v_readfirstlane_b32 s8, v135
	s_lshl_b64 s[80:81], s[76:77], 11
	global_load_lds_dwordx4 v[0:1], off
	s_mov_b32 m0, s8
	s_add_u32 s8, s56, s80
	v_lshl_add_u64 v[2:3], v[0:1], 0, s[6:7]
	s_addc_u32 s9, s57, s81
	global_load_lds_dwordx4 v[2:3], off
	v_lshl_add_u64 v[2:3], s[8:9], 0, v[128:129]
	v_readfirstlane_b32 s8, v136
	s_mov_b32 m0, s8
	v_readfirstlane_b32 s8, v137
	global_load_lds_dwordx4 v[2:3], off
	s_mov_b32 m0, s8
	s_or_b32 s8, s74, 0x80
	s_ashr_i32 s9, s8, 31
	s_lshl_b64 s[8:9], s[8:9], 11
	s_add_u32 s8, s88, s8
	v_lshl_add_u64 v[4:5], v[2:3], 0, s[6:7]
	s_addc_u32 s9, s89, s9
	global_load_lds_dwordx4 v[4:5], off
	v_lshl_add_u64 v[4:5], s[8:9], 0, v[128:129]
	v_readfirstlane_b32 s8, v138
	s_mov_b32 m0, s8
	v_readfirstlane_b32 s8, v139
	global_load_lds_dwordx4 v[4:5], off
	s_mov_b32 m0, s8
	s_or_b32 s8, s76, 0x80
	s_ashr_i32 s9, s8, 31
	s_lshl_b64 s[8:9], s[8:9], 11
	s_add_u32 s8, s56, s8
	s_addc_u32 s9, s57, s9
	v_lshl_add_u64 v[6:7], v[4:5], 0, s[6:7]
	v_lshl_add_u64 v[132:133], s[8:9], 0, v[128:129]
	v_readfirstlane_b32 s8, v140
	global_load_lds_dwordx4 v[6:7], off
	s_mov_b32 m0, s8
	v_readfirstlane_b32 s8, v141
	global_load_lds_dwordx4 v[132:133], off
	v_lshl_add_u64 v[6:7], v[132:133], 0, s[6:7]
	s_mov_b32 m0, s8
	s_and_b64 vcc, exec, s[0:1]
	global_load_lds_dwordx4 v[6:7], off
	v_readfirstlane_b32 s8, v154
	v_lshl_add_u64 v[6:7], v[0:1], 0, s[10:11]
	s_mov_b32 m0, s8
	v_readfirstlane_b32 s8, v155
	global_load_lds_dwordx4 v[6:7], off
	v_lshl_add_u64 v[0:1], v[0:1], 0, s[14:15]
	s_mov_b32 m0, s8
	v_readfirstlane_b32 s8, v142
	global_load_lds_dwordx4 v[0:1], off
	v_lshl_add_u64 v[0:1], v[2:3], 0, s[10:11]
	s_mov_b32 m0, s8
	v_readfirstlane_b32 s8, v143
	global_load_lds_dwordx4 v[0:1], off
	v_lshl_add_u64 v[0:1], v[2:3], 0, s[14:15]
	s_mov_b32 m0, s8
	v_readfirstlane_b32 s8, v156
	global_load_lds_dwordx4 v[0:1], off
	v_lshl_add_u64 v[0:1], v[4:5], 0, s[10:11]
	s_mov_b32 m0, s8
	v_readfirstlane_b32 s8, v157
	global_load_lds_dwordx4 v[0:1], off
	v_lshl_add_u64 v[0:1], v[4:5], 0, s[14:15]
	s_mov_b32 m0, s8
	s_add_u32 s78, s52, s78
	global_load_lds_dwordx4 v[0:1], off
	s_cbranch_vccnz .LBB0_404
	s_barrier
.LBB0_404:
	s_waitcnt vmcnt(10)
	s_barrier
	s_waitcnt vmcnt(6)
	s_addc_u32 s79, s53, s79
	s_add_u32 s80, s52, s80
	v_mov_b32_e32 v0, 0
	s_addc_u32 s81, s53, s81
	s_mov_b32 s59, -2
	v_mov_b32_e32 v1, v0
	v_mov_b32_e32 v2, v0
	v_mov_b32_e32 v3, v0
	v_mov_b32_e32 v4, v0
	v_mov_b32_e32 v5, v0
	v_mov_b32_e32 v6, v0
	v_mov_b32_e32 v7, v0
	v_mov_b32_e32 v8, v0
	v_mov_b32_e32 v9, v0
	v_mov_b32_e32 v10, v0
	v_mov_b32_e32 v11, v0
	v_mov_b32_e32 v12, v0
	v_mov_b32_e32 v13, v0
	v_mov_b32_e32 v14, v0
	v_mov_b32_e32 v15, v0
	v_mov_b32_e32 v16, v0
	v_mov_b32_e32 v17, v0
	v_mov_b32_e32 v18, v0
	v_mov_b32_e32 v19, v0
	v_mov_b32_e32 v20, v0
	v_mov_b32_e32 v21, v0
	v_mov_b32_e32 v22, v0
	v_mov_b32_e32 v23, v0
	v_mov_b32_e32 v24, v0
	v_mov_b32_e32 v25, v0
	v_mov_b32_e32 v26, v0
	v_mov_b32_e32 v27, v0
	v_mov_b32_e32 v28, v0
	v_mov_b32_e32 v29, v0
	v_mov_b32_e32 v30, v0
	v_mov_b32_e32 v31, v0
	v_mov_b32_e32 v32, v0
	v_mov_b32_e32 v33, v0
	v_mov_b32_e32 v34, v0
	v_mov_b32_e32 v35, v0
	v_mov_b32_e32 v36, v0
	v_mov_b32_e32 v37, v0
	v_mov_b32_e32 v38, v0
	v_mov_b32_e32 v39, v0
	v_mov_b32_e32 v40, v0
	v_mov_b32_e32 v41, v0
	v_mov_b32_e32 v42, v0
	v_mov_b32_e32 v43, v0
	v_mov_b32_e32 v44, v0
	v_mov_b32_e32 v45, v0
	v_mov_b32_e32 v46, v0
	v_mov_b32_e32 v47, v0
	v_mov_b32_e32 v48, v0
	v_mov_b32_e32 v49, v0
	v_mov_b32_e32 v50, v0
	v_mov_b32_e32 v51, v0
	v_mov_b32_e32 v52, v0
	v_mov_b32_e32 v53, v0
	v_mov_b32_e32 v54, v0
	v_mov_b32_e32 v55, v0
	v_mov_b32_e32 v56, v0
	v_mov_b32_e32 v57, v0
	v_mov_b32_e32 v58, v0
	v_mov_b32_e32 v59, v0
	v_mov_b32_e32 v60, v0
	v_mov_b32_e32 v61, v0
	v_mov_b32_e32 v62, v0
	v_mov_b32_e32 v63, v0
	v_mov_b32_e32 v64, v0
	v_mov_b32_e32 v65, v0
	v_mov_b32_e32 v66, v0
	v_mov_b32_e32 v67, v0
	v_mov_b32_e32 v68, v0
	v_mov_b32_e32 v69, v0
	v_mov_b32_e32 v70, v0
	v_mov_b32_e32 v71, v0
	v_mov_b32_e32 v72, v0
	v_mov_b32_e32 v73, v0
	v_mov_b32_e32 v74, v0
	v_mov_b32_e32 v75, v0
	v_mov_b32_e32 v76, v0
	v_mov_b32_e32 v77, v0
	v_mov_b32_e32 v78, v0
	v_mov_b32_e32 v79, v0
	v_mov_b32_e32 v80, v0
	v_mov_b32_e32 v81, v0
	v_mov_b32_e32 v82, v0
	v_mov_b32_e32 v83, v0
	v_mov_b32_e32 v84, v0
	v_mov_b32_e32 v85, v0
	v_mov_b32_e32 v86, v0
	v_mov_b32_e32 v87, v0
	v_mov_b32_e32 v88, v0
	v_mov_b32_e32 v89, v0
	v_mov_b32_e32 v90, v0
	v_mov_b32_e32 v91, v0
	v_mov_b32_e32 v92, v0
	v_mov_b32_e32 v93, v0
	v_mov_b32_e32 v94, v0
	v_mov_b32_e32 v95, v0
	v_mov_b32_e32 v96, v0
	v_mov_b32_e32 v97, v0
	v_mov_b32_e32 v98, v0
	v_mov_b32_e32 v99, v0
	v_mov_b32_e32 v100, v0
	v_mov_b32_e32 v101, v0
	v_mov_b32_e32 v102, v0
	v_mov_b32_e32 v103, v0
	v_mov_b32_e32 v104, v0
	v_mov_b32_e32 v105, v0
	v_mov_b32_e32 v106, v0
	v_mov_b32_e32 v107, v0
	v_mov_b32_e32 v108, v0
	v_mov_b32_e32 v109, v0
	v_mov_b32_e32 v110, v0
	v_mov_b32_e32 v111, v0
	v_mov_b32_e32 v112, v0
	v_mov_b32_e32 v113, v0
	v_mov_b32_e32 v114, v0
	v_mov_b32_e32 v115, v0
	v_mov_b32_e32 v116, v0
	v_mov_b32_e32 v117, v0
	v_mov_b32_e32 v118, v0
	v_mov_b32_e32 v119, v0
	v_mov_b32_e32 v120, v0
	v_mov_b32_e32 v121, v0
	v_mov_b32_e32 v122, v0
	v_mov_b32_e32 v123, v0
	v_mov_b32_e32 v124, v0
	v_mov_b32_e32 v125, v0
	v_mov_b32_e32 v126, v0
	v_mov_b32_e32 v127, v0
	s_barrier

; #define WAIT_V(n) asm volatile("s_waitcnt vmcnt(" #n ")" ::: "memory")
; #define BAR __builtin_amdgcn_s_barrier()
; template <int N, int K, int EPI>
; __device__ __forceinline__ void gemm_phase(const bf16* __restrict__ A, const bf16* __restrict__ Bt, float* __restrict__ outf, bf16* __restrict__ outb,
;                            const float* __restrict__ ropec, const int W) {
;     ...
;     f32x4 acc[2][2][4][2] = {};
;     bf16x8 At[4][2], B0[2][2], B1[2][2];
;     STAGE(SB(0, 0), Bt, bcol, 0); STAGE(SA(0, 0), A, brow, 0);
;     STAGE(SB(0, 1), Bt, bcol + HALF, 0); STAGE(SA(0, 1), A, brow + HALF, 0);
;     if (wr == 1) BAR;
;     WAIT_V(4); BAR;
;     STAGE(SB(1, 0), Bt, bcol, 1); STAGE(SA(1, 0), A, brow, 1); STAGE(SB(1, 1), Bt, bcol + HALF, 1);
;     WAIT_V(6); BAR;
.LBB0_423:
	s_ashr_i32 s55, s55, 3
	s_add_i32 s55, s71, s55
	s_ashr_i32 s68, s55, 31
	s_lshr_b32 s68, s68, 27
	s_add_i32 s68, s55, s68
	s_and_b32 s69, s68, 0xffe0
	s_sub_i32 s55, s55, s69
	s_bfe_i32 s69, s55, 0x80000
	s_bfe_u32 s69, s69, 0x3000c
	s_add_i32 s69, s55, s69
	s_bfe_i32 s70, s69, 0x80000
	s_and_b32 s69, s69, 0xf8
	s_sub_i32 s55, s55, s69
	s_sext_i32_i8 s55, s55
	s_lshl_b32 s68, s68, 6
	s_sext_i32_i16 s71, s70
	s_and_b32 s68, s68, 0xfffff800
	s_lshl_b32 s55, s55, 8
	s_add_i32 s70, s55, s68
	s_lshl_b32 s55, s71, 5
	s_and_b32 s68, s55, 0xffffff00
	s_ashr_i32 s69, s68, 31
	s_lshl_b64 s[72:73], s[68:69], 13
	s_add_u32 s74, s86, s72
	s_addc_u32 s75, s87, s73
	s_ashr_i32 s71, s70, 31
	v_lshl_add_u64 v[0:1], s[74:75], 0, v[128:129]
	v_readfirstlane_b32 s55, v134
	s_lshl_b64 s[74:75], s[70:71], 13
	s_mov_b32 m0, s55
	v_readfirstlane_b32 s55, v135
	s_add_u32 s76, s36, s74
	global_load_lds_dwordx4 v[0:1], off
	v_lshl_add_u64 v[2:3], v[0:1], 0, s[6:7]
	s_mov_b32 m0, s55
	s_addc_u32 s77, s37, s75
	global_load_lds_dwordx4 v[2:3], off
	v_lshl_add_u64 v[2:3], s[76:77], 0, v[128:129]
	s_or_b32 s76, s68, 0x80
	s_ashr_i32 s77, s76, 31
	v_readfirstlane_b32 s55, v136
	s_lshl_b64 s[76:77], s[76:77], 13
	s_mov_b32 m0, s55
	v_readfirstlane_b32 s55, v137
	s_add_u32 s76, s86, s76
	global_load_lds_dwordx4 v[2:3], off
	v_lshl_add_u64 v[4:5], v[2:3], 0, s[6:7]
	s_mov_b32 m0, s55
	s_addc_u32 s77, s87, s77
	global_load_lds_dwordx4 v[4:5], off
	v_lshl_add_u64 v[4:5], s[76:77], 0, v[128:129]
	s_or_b32 s76, s70, 0x80
	s_ashr_i32 s77, s76, 31
	v_readfirstlane_b32 s55, v138
	s_lshl_b64 s[76:77], s[76:77], 13
	s_mov_b32 m0, s55
	v_readfirstlane_b32 s55, v139
	s_add_u32 s76, s36, s76
	global_load_lds_dwordx4 v[4:5], off
	v_lshl_add_u64 v[6:7], v[4:5], 0, s[6:7]
	s_mov_b32 m0, s55
	s_addc_u32 s77, s37, s77
	v_readfirstlane_b32 s55, v140
	global_load_lds_dwordx4 v[6:7], off
	v_lshl_add_u64 v[132:133], s[76:77], 0, v[128:129]
	s_mov_b32 m0, s55
	v_readfirstlane_b32 s55, v141
	global_load_lds_dwordx4 v[132:133], off
	v_lshl_add_u64 v[6:7], v[132:133], 0, s[6:7]
	s_mov_b32 m0, s55
	s_and_b64 vcc, exec, s[0:1]
	global_load_lds_dwordx4 v[6:7], off
	v_readfirstlane_b32 s55, v154
	v_lshl_add_u64 v[6:7], v[0:1], 0, s[8:9]
	s_mov_b32 m0, s55
	v_readfirstlane_b32 s55, v155
	global_load_lds_dwordx4 v[6:7], off
	v_lshl_add_u64 v[0:1], v[0:1], 0, s[10:11]
	s_mov_b32 m0, s55
	v_readfirstlane_b32 s55, v142
	global_load_lds_dwordx4 v[0:1], off
	v_lshl_add_u64 v[0:1], v[2:3], 0, s[8:9]
	s_mov_b32 m0, s55
	v_readfirstlane_b32 s55, v143
	global_load_lds_dwordx4 v[0:1], off
	v_lshl_add_u64 v[0:1], v[2:3], 0, s[10:11]
	s_mov_b32 m0, s55
	v_readfirstlane_b32 s55, v156
	global_load_lds_dwordx4 v[0:1], off
	v_lshl_add_u64 v[0:1], v[4:5], 0, s[8:9]
	s_mov_b32 m0, s55
	v_readfirstlane_b32 s55, v157
	global_load_lds_dwordx4 v[0:1], off
	v_lshl_add_u64 v[0:1], v[4:5], 0, s[10:11]
	s_mov_b32 m0, s55
	s_add_u32 s72, s52, s72
	global_load_lds_dwordx4 v[0:1], off
	s_cbranch_vccnz .LBB0_425
	s_barrier
.LBB0_425:
	s_waitcnt vmcnt(10)
	s_barrier
	s_waitcnt vmcnt(6)
	s_addc_u32 s73, s53, s73
	s_add_u32 s74, s52, s74
	v_mov_b32_e32 v0, 0
	s_addc_u32 s75, s53, s75
	s_mov_b32 s55, -2
	v_mov_b32_e32 v1, v0
	v_mov_b32_e32 v2, v0
	v_mov_b32_e32 v3, v0
	v_mov_b32_e32 v4, v0
	v_mov_b32_e32 v5, v0
	v_mov_b32_e32 v6, v0
	v_mov_b32_e32 v7, v0
	v_mov_b32_e32 v8, v0
	v_mov_b32_e32 v9, v0
	v_mov_b32_e32 v10, v0
	v_mov_b32_e32 v11, v0
	v_mov_b32_e32 v12, v0
	v_mov_b32_e32 v13, v0
	v_mov_b32_e32 v14, v0
	v_mov_b32_e32 v15, v0
	v_mov_b32_e32 v16, v0
	v_mov_b32_e32 v17, v0
	v_mov_b32_e32 v18, v0
	v_mov_b32_e32 v19, v0
	v_mov_b32_e32 v20, v0
	v_mov_b32_e32 v21, v0
	v_mov_b32_e32 v22, v0
	v_mov_b32_e32 v23, v0
	v_mov_b32_e32 v24, v0
	v_mov_b32_e32 v25, v0
	v_mov_b32_e32 v26, v0
	v_mov_b32_e32 v27, v0
	v_mov_b32_e32 v28, v0
	v_mov_b32_e32 v29, v0
	v_mov_b32_e32 v30, v0
	v_mov_b32_e32 v31, v0
	v_mov_b32_e32 v32, v0
	v_mov_b32_e32 v33, v0
	v_mov_b32_e32 v34, v0
	v_mov_b32_e32 v35, v0
	v_mov_b32_e32 v36, v0
	v_mov_b32_e32 v37, v0
	v_mov_b32_e32 v38, v0
	v_mov_b32_e32 v39, v0
	v_mov_b32_e32 v40, v0
	v_mov_b32_e32 v41, v0
	v_mov_b32_e32 v42, v0
	v_mov_b32_e32 v43, v0
	v_mov_b32_e32 v44, v0
	v_mov_b32_e32 v45, v0
	v_mov_b32_e32 v46, v0
	v_mov_b32_e32 v47, v0
	v_mov_b32_e32 v48, v0
	v_mov_b32_e32 v49, v0
	v_mov_b32_e32 v50, v0
	v_mov_b32_e32 v51, v0
	v_mov_b32_e32 v52, v0
	v_mov_b32_e32 v53, v0
	v_mov_b32_e32 v54, v0
	v_mov_b32_e32 v55, v0
	v_mov_b32_e32 v56, v0
	v_mov_b32_e32 v57, v0
	v_mov_b32_e32 v58, v0
	v_mov_b32_e32 v59, v0
	v_mov_b32_e32 v60, v0
	v_mov_b32_e32 v61, v0
	v_mov_b32_e32 v62, v0
	v_mov_b32_e32 v63, v0
	v_mov_b32_e32 v64, v0
	v_mov_b32_e32 v65, v0
	v_mov_b32_e32 v66, v0
	v_mov_b32_e32 v67, v0
	v_mov_b32_e32 v68, v0
	v_mov_b32_e32 v69, v0
	v_mov_b32_e32 v70, v0
	v_mov_b32_e32 v71, v0
	v_mov_b32_e32 v72, v0
	v_mov_b32_e32 v73, v0
	v_mov_b32_e32 v74, v0
	v_mov_b32_e32 v75, v0
	v_mov_b32_e32 v76, v0
	v_mov_b32_e32 v77, v0
	v_mov_b32_e32 v78, v0
	v_mov_b32_e32 v79, v0
	v_mov_b32_e32 v80, v0
	v_mov_b32_e32 v81, v0
	v_mov_b32_e32 v82, v0
	v_mov_b32_e32 v83, v0
	v_mov_b32_e32 v84, v0
	v_mov_b32_e32 v85, v0
	v_mov_b32_e32 v86, v0
	v_mov_b32_e32 v87, v0
	v_mov_b32_e32 v88, v0
	v_mov_b32_e32 v89, v0
	v_mov_b32_e32 v90, v0
	v_mov_b32_e32 v91, v0
	v_mov_b32_e32 v92, v0
	v_mov_b32_e32 v93, v0
	v_mov_b32_e32 v94, v0
	v_mov_b32_e32 v95, v0
	v_mov_b32_e32 v96, v0
	v_mov_b32_e32 v97, v0
	v_mov_b32_e32 v98, v0
	v_mov_b32_e32 v99, v0
	v_mov_b32_e32 v100, v0
	v_mov_b32_e32 v101, v0
	v_mov_b32_e32 v102, v0
	v_mov_b32_e32 v103, v0
	v_mov_b32_e32 v104, v0
	v_mov_b32_e32 v105, v0
	v_mov_b32_e32 v106, v0
	v_mov_b32_e32 v107, v0
	v_mov_b32_e32 v108, v0
	v_mov_b32_e32 v109, v0
	v_mov_b32_e32 v110, v0
	v_mov_b32_e32 v111, v0
	v_mov_b32_e32 v112, v0
	v_mov_b32_e32 v113, v0
	v_mov_b32_e32 v114, v0
	v_mov_b32_e32 v115, v0
	v_mov_b32_e32 v116, v0
	v_mov_b32_e32 v117, v0
	v_mov_b32_e32 v118, v0
	v_mov_b32_e32 v119, v0
	v_mov_b32_e32 v120, v0
	v_mov_b32_e32 v121, v0
	v_mov_b32_e32 v122, v0
	v_mov_b32_e32 v123, v0
	v_mov_b32_e32 v124, v0
	v_mov_b32_e32 v125, v0
	v_mov_b32_e32 v126, v0
	v_mov_b32_e32 v127, v0
	s_barrier
